# odd attention step rescheduled: QK MFMAs head-major, softmax exp/cvt/row-sum VALU placed one per MFMA issue gap (same instructions and registers)
# speedup vs baseline: 1.0020x; 1.0020x over previous
; DI unsigned pk2(float lo, float hi) { f32x2 v = {lo, hi}; bf16x2_t b = __builtin_convertvector(v, bf16x2_t); return __builtin_bit_cast(unsigned, b); }
; #define MFMA16(a, b, c) __builtin_amdgcn_mfma_f32_16x16x32_bf16((a), (b), (c), 0, 0, 0)
; DI void attn_group4(f32x4 (&o)[4][4], const float (&mref)[4], float (&ls)[4], const bf16x8 (&q)[4][2], bf16x8 k00, bf16x8 k01, bf16x8 k10, bf16x8 k11,
;                     bf16x8 v0, bf16x8 v1, bf16x8 v2, bf16x8 v3) {
;     const f32x4 z = {0.f, 0.f, 0.f, 0.f};
;     constexpr float C = 0.125f * LOG2E;
;     f32x4 s0[4], s1[4];
;     __builtin_amdgcn_s_setprio(1);
; #pragma unroll
;     for (int h = 0; h < 4; ++h) { s0[h] = MFMA16(k00, q[h][0], z); s1[h] = MFMA16(k10, q[h][0], z); }
; #pragma unroll
;     for (int h = 0; h < 4; ++h) { s0[h] = MFMA16(k01, q[h][1], s0[h]); s1[h] = MFMA16(k11, q[h][1], s1[h]); }
;     __builtin_amdgcn_s_setprio(0);
;     bf16x8 pb[4];
; #pragma unroll
;     for (int h = 0; h < 4; ++h) {
;         f32x4 p0, p1;
; #pragma unroll
;         for (int e = 0; e < 4; ++e) { p0[e] = __builtin_amdgcn_exp2f(__builtin_fmaf(s0[h][e], C, -mref[h])); p1[e] = __builtin_amdgcn_exp2f(__builtin_fmaf(s1[h][e], C, -mref[h])); }
;         ls[h] += ((p0[0] + p0[1]) + (p0[2] + p0[3])) + ((p1[0] + p1[1]) + (p1[2] + p1[3]));
;         u32x4 pw; pw.x = pk2(p0[0], p0[1]); pw.y = pk2(p0[2], p0[3]); pw.z = pk2(p1[0], p1[1]); pw.w = pk2(p1[2], p1[3]);
;         pb[h] = __builtin_bit_cast(bf16x8, pw);
;     }
;     __builtin_amdgcn_s_setprio(1);
; #pragma unroll
;     for (int h = 0; h < 4; ++h) { o[h][0] = MFMA16(v0, pb[h], o[h][0]); o[h][1] = MFMA16(v1, pb[h], o[h][1]); o[h][2] = MFMA16(v2, pb[h], o[h][2]); o[h][3] = MFMA16(v3, pb[h], o[h][3]); }
;     __builtin_amdgcn_s_setprio(0);
; }
.Latto_nodma:
	s_waitcnt lgkmcnt(7)
	v_mfma_f32_16x16x32_bf16 v[152:155], v[98:101], v[2:5], v[228:231]
	s_waitcnt lgkmcnt(5)
	v_mfma_f32_16x16x32_bf16 v[156:159], v[112:115], v[2:5], v[228:231]
	v_mfma_f32_16x16x32_bf16 v[152:155], v[108:111], v[6:9], v[152:155]
	s_waitcnt lgkmcnt(4)
	v_mfma_f32_16x16x32_bf16 v[156:159], v[116:119], v[6:9], v[156:159]
	v_mfma_f32_16x16x32_bf16 v[170:173], v[98:101], v[10:13], v[232:235]
	v_mfma_f32_16x16x32_bf16 v[174:177], v[112:115], v[10:13], v[232:235]
	v_mfma_f32_16x16x32_bf16 v[170:173], v[108:111], v[14:17], v[170:173]
	v_mfma_f32_16x16x32_bf16 v[174:177], v[116:119], v[14:17], v[174:177]
	v_mfma_f32_16x16x32_bf16 v[188:191], v[98:101], v[18:21], v[236:239]
	v_mfma_f32_16x16x32_bf16 v[196:199], v[112:115], v[18:21], v[236:239]
	v_mfma_f32_16x16x32_bf16 v[188:191], v[108:111], v[22:25], v[188:191]
	v_exp_f32_e32 v161, v152
	v_mfma_f32_16x16x32_bf16 v[196:199], v[116:119], v[22:25], v[196:199]
	v_exp_f32_e32 v167, v156
	v_mfma_f32_16x16x32_bf16 v[98:101], v[98:101], v[42:45], v[240:243]
	v_exp_f32_e32 v179, v153
	v_mfma_f32_16x16x32_bf16 v[112:115], v[112:115], v[42:45], v[240:243]
	v_exp_f32_e32 v185, v157
	v_mfma_f32_16x16x32_bf16 v[98:101], v[108:111], v[46:49], v[98:101]
	v_exp_f32_e32 v213, v154
	v_mfma_f32_16x16x32_bf16 v[200:203], v[116:119], v[46:49], v[112:115]
	v_exp_f32_e32 v215, v158
	v_exp_f32_e32 v217, v155
	v_exp_f32_e32 v219, v159
	v_cvt_pk_bf16_f32 v152, v161, v179
	v_cvt_pk_bf16_f32 v153, v213, v217
	v_cvt_pk_bf16_f32 v154, v167, v185
	v_cvt_pk_bf16_f32 v155, v215, v219
	v_exp_f32_e32 v160, v170
	v_exp_f32_e32 v166, v174
	s_waitcnt lgkmcnt(3)
	v_mfma_f32_16x16x32_bf16 v[94:97], v[136:139], v[152:155], v[94:97]
	v_exp_f32_e32 v178, v171
	s_waitcnt lgkmcnt(2)
	v_mfma_f32_16x16x32_bf16 v[90:93], v[140:143], v[152:155], v[90:93]
	v_exp_f32_e32 v184, v175
	s_waitcnt lgkmcnt(1)
	v_mfma_f32_16x16x32_bf16 v[86:89], v[144:147], v[152:155], v[86:89]
	v_exp_f32_e32 v212, v172
	s_waitcnt lgkmcnt(0)
	v_mfma_f32_16x16x32_bf16 v[82:85], v[148:151], v[152:155], v[82:85]
	v_exp_f32_e32 v214, v176
	v_exp_f32_e32 v216, v173
	v_exp_f32_e32 v218, v177
	v_cvt_pk_bf16_f32 v156, v160, v178
	v_cvt_pk_bf16_f32 v157, v212, v216
	v_cvt_pk_bf16_f32 v158, v166, v184
	v_cvt_pk_bf16_f32 v159, v214, v218
	v_exp_f32_e32 v117, v188
	v_exp_f32_e32 v109, v196
	v_mfma_f32_16x16x32_bf16 v[78:81], v[136:139], v[156:159], v[78:81]
	v_exp_f32_e32 v221, v189
	v_mfma_f32_16x16x32_bf16 v[74:77], v[140:143], v[156:159], v[74:77]
	v_exp_f32_e32 v113, v197
	v_mfma_f32_16x16x32_bf16 v[70:73], v[144:147], v[156:159], v[70:73]
	v_exp_f32_e32 v119, v190
	v_mfma_f32_16x16x32_bf16 v[66:69], v[148:151], v[156:159], v[66:69]
	v_exp_f32_e32 v111, v198
	v_exp_f32_e32 v223, v191
	v_exp_f32_e32 v115, v199
	v_cvt_pk_bf16_f32 v170, v117, v221
	v_cvt_pk_bf16_f32 v171, v119, v223
	v_cvt_pk_bf16_f32 v172, v109, v113
	v_cvt_pk_bf16_f32 v173, v111, v115
	v_exp_f32_e32 v116, v98
	v_exp_f32_e32 v108, v200
	v_mfma_f32_16x16x32_bf16 v[62:65], v[136:139], v[170:173], v[62:65]
	v_exp_f32_e32 v220, v99
	v_mfma_f32_16x16x32_bf16 v[58:61], v[140:143], v[170:173], v[58:61]
	v_exp_f32_e32 v112, v201
	v_mfma_f32_16x16x32_bf16 v[54:57], v[144:147], v[170:173], v[54:57]
	v_exp_f32_e32 v118, v100
	v_mfma_f32_16x16x32_bf16 v[50:53], v[148:151], v[170:173], v[50:53]
	v_exp_f32_e32 v110, v202
	v_exp_f32_e32 v222, v101
	v_exp_f32_e32 v114, v203
	v_cvt_pk_bf16_f32 v98, v116, v220
	v_cvt_pk_bf16_f32 v99, v118, v222
	v_cvt_pk_bf16_f32 v100, v108, v112
	v_cvt_pk_bf16_f32 v101, v110, v114
	v_add_u32_e32 v152, 0x2c00, v168
	v_add_u32_e32 v156, 0x3800, v168
	v_mfma_f32_16x16x32_bf16 v[38:41], v[136:139], v[98:101], v[38:41]
	v_pk_add_f32 v[160:161], v[160:161], v[178:179]
	v_mfma_f32_16x16x32_bf16 v[34:37], v[140:143], v[98:101], v[34:37]
	ds_read_b128 v[136:139], v165 offset:4608
	ds_read_b128 v[140:143], v165 offset:5120
	v_mfma_f32_16x16x32_bf16 v[30:33], v[144:147], v[98:101], v[30:33]
	v_pk_add_f32 v[178:179], v[212:213], v[216:217]
	v_mfma_f32_16x16x32_bf16 v[26:29], v[148:151], v[98:101], v[26:29]
	ds_read_b128 v[144:147], v165 offset:6912
	ds_read_b128 v[148:151], v165 offset:7424
	s_waitcnt lgkmcnt(3)
	v_mfma_f32_16x16x32_bf16 v[174:177], v[136:139], v[2:5], v[228:231]
	ds_read2_b64 v[98:101], v195 offset0:192 offset1:224
	ds_read2_b64 v[152:155], v152 offset0:96 offset1:128
	s_waitcnt lgkmcnt(3)
	v_mfma_f32_16x16x32_bf16 v[188:191], v[144:147], v[2:5], v[228:231]
	ds_read2_b64 v[156:159], v156 offset1:32
	v_add_u32_e32 v165, 0x4000, v168
	v_mfma_f32_16x16x32_bf16 v[174:177], v[140:143], v[6:9], v[174:177]
	ds_read2_b64 v[170:173], v165 offset0:32 offset1:64
	s_waitcnt lgkmcnt(4)
; DI unsigned pk2(float lo, float hi) { f32x2 v = {lo, hi}; bf16x2_t b = __builtin_convertvector(v, bf16x2_t); return __builtin_bit_cast(unsigned, b); }
; #define MFMA16(a, b, c) __builtin_amdgcn_mfma_f32_16x16x32_bf16((a), (b), (c), 0, 0, 0)
; DI void attn_group4(f32x4 (&o)[4][4], const float (&mref)[4], float (&ls)[4], const bf16x8 (&q)[4][2], bf16x8 k00, bf16x8 k01, bf16x8 k10, bf16x8 k11,
;                     bf16x8 v0, bf16x8 v1, bf16x8 v2, bf16x8 v3) {
;     const f32x4 z = {0.f, 0.f, 0.f, 0.f};
;     constexpr float C = 0.125f * LOG2E;
;     f32x4 s0[4], s1[4];
;     __builtin_amdgcn_s_setprio(1);
; #pragma unroll
;     for (int h = 0; h < 4; ++h) { s0[h] = MFMA16(k00, q[h][0], z); s1[h] = MFMA16(k10, q[h][0], z); }
; #pragma unroll
;     for (int h = 0; h < 4; ++h) { s0[h] = MFMA16(k01, q[h][1], s0[h]); s1[h] = MFMA16(k11, q[h][1], s1[h]); }
;     __builtin_amdgcn_s_setprio(0);
;     bf16x8 pb[4];
; #pragma unroll
;     for (int h = 0; h < 4; ++h) {
;         f32x4 p0, p1;
; #pragma unroll
;         for (int e = 0; e < 4; ++e) { p0[e] = __builtin_amdgcn_exp2f(__builtin_fmaf(s0[h][e], C, -mref[h])); p1[e] = __builtin_amdgcn_exp2f(__builtin_fmaf(s1[h][e], C, -mref[h])); }
;         ls[h] += ((p0[0] + p0[1]) + (p0[2] + p0[3])) + ((p1[0] + p1[1]) + (p1[2] + p1[3]));
;         u32x4 pw; pw.x = pk2(p0[0], p0[1]); pw.y = pk2(p0[2], p0[3]); pw.z = pk2(p1[0], p1[1]); pw.w = pk2(p1[2], p1[3]);
;         pb[h] = __builtin_bit_cast(bf16x8, pw);
;     }
;     __builtin_amdgcn_s_setprio(1);
; #pragma unroll
;     for (int h = 0; h < 4; ++h) { o[h][0] = MFMA16(v0, pb[h], o[h][0]); o[h][1] = MFMA16(v1, pb[h], o[h][1]); o[h][2] = MFMA16(v2, pb[h], o[h][2]); o[h][3] = MFMA16(v3, pb[h], o[h][3]); }
;     __builtin_amdgcn_s_setprio(0);
; }
; DI void attn_odd_lds(Frame& F, const float* gk  , const float* gq  , bool with_ctx) {
;     ...
;         for (int s = 0; s < n; ++s) {
	v_mfma_f32_16x16x32_bf16 v[188:191], v[148:151], v[6:9], v[188:191]
	v_pk_add_f32 v[160:161], v[160:161], v[178:179]
	v_mfma_f32_16x16x32_bf16 v[196:199], v[136:139], v[10:13], v[232:235]
	v_pk_add_f32 v[166:167], v[166:167], v[184:185]
	v_mfma_f32_16x16x32_bf16 v[200:203], v[144:147], v[10:13], v[232:235]
	v_pk_add_f32 v[178:179], v[214:215], v[218:219]
	v_mfma_f32_16x16x32_bf16 v[196:199], v[140:143], v[14:17], v[196:199]
	v_exp_f32_e32 v225, v176
	v_mfma_f32_16x16x32_bf16 v[200:203], v[148:151], v[14:17], v[200:203]
	v_exp_f32_e32 v175, v175
	v_mfma_f32_16x16x32_bf16 v[204:207], v[136:139], v[18:21], v[236:239]
	v_exp_f32_e32 v177, v177
	v_mfma_f32_16x16x32_bf16 v[208:211], v[144:147], v[18:21], v[236:239]
	v_exp_f32_e32 v227, v190
	v_mfma_f32_16x16x32_bf16 v[204:207], v[140:143], v[22:25], v[204:207]
	v_exp_f32_e32 v189, v189
	v_mfma_f32_16x16x32_bf16 v[208:211], v[148:151], v[22:25], v[208:211]
	v_exp_f32_e32 v191, v191
	v_mfma_f32_16x16x32_bf16 v[136:139], v[136:139], v[42:45], v[240:243]
	v_pk_add_f32 v[166:167], v[166:167], v[178:179]
	v_mfma_f32_16x16x32_bf16 v[144:147], v[144:147], v[42:45], v[240:243]
	v_pk_add_f32 v[160:161], v[160:161], v[166:167]
	v_mfma_f32_16x16x32_bf16 v[136:139], v[140:143], v[46:49], v[136:139]
	v_exp_f32_e32 v224, v198
	v_mfma_f32_16x16x32_bf16 v[140:143], v[148:151], v[46:49], v[144:147]
	v_exp_f32_e32 v149, v174
	v_exp_f32_e32 v151, v188
	v_exp_f32_e32 v174, v197
	v_exp_f32_e32 v148, v196
	v_cvt_pk_bf16_f32 v146, v151, v189
	v_cvt_pk_bf16_f32 v147, v227, v191
	v_cvt_pk_bf16_f32 v144, v149, v175
	v_cvt_pk_bf16_f32 v145, v225, v177
	v_exp_f32_e32 v176, v199
	v_pk_add_f32 v[106:107], v[106:107], v[160:161]
	s_waitcnt lgkmcnt(3)
	v_mfma_f32_16x16x32_bf16 v[94:97], v[98:101], v[144:147], v[94:97]
	v_pk_add_f32 v[166:167], v[224:225], v[176:177]
	s_waitcnt lgkmcnt(2)
	v_mfma_f32_16x16x32_bf16 v[90:93], v[152:155], v[144:147], v[90:93]
	v_pk_add_f32 v[160:161], v[148:149], v[174:175]
	s_waitcnt lgkmcnt(1)
	v_mfma_f32_16x16x32_bf16 v[86:89], v[156:159], v[144:147], v[86:89]
	v_exp_f32_e32 v188, v201
	s_waitcnt lgkmcnt(0)
	v_mfma_f32_16x16x32_bf16 v[82:85], v[170:173], v[144:147], v[82:85]
	v_exp_f32_e32 v226, v202
	v_exp_f32_e32 v150, v200
	v_exp_f32_e32 v190, v203
	v_pk_add_f32 v[160:161], v[160:161], v[166:167]
	v_pk_add_f32 v[166:167], v[150:151], v[188:189]
	v_cvt_pk_bf16_f32 v150, v150, v188
	v_cvt_pk_bf16_f32 v151, v226, v190
	v_cvt_pk_bf16_f32 v148, v148, v174
	v_cvt_pk_bf16_f32 v149, v224, v176
	v_pk_add_f32 v[178:179], v[226:227], v[190:191]
	v_pk_add_f32 v[166:167], v[166:167], v[178:179]
	v_mfma_f32_16x16x32_bf16 v[78:81], v[98:101], v[148:151], v[78:81]
	v_pk_add_f32 v[160:161], v[160:161], v[166:167]
	v_mfma_f32_16x16x32_bf16 v[74:77], v[152:155], v[148:151], v[74:77]
	v_pk_add_f32 v[106:107], v[106:107], v[160:161]
	v_mfma_f32_16x16x32_bf16 v[70:73], v[156:159], v[148:151], v[70:73]
	v_exp_f32_e32 v161, v204
	v_mfma_f32_16x16x32_bf16 v[66:69], v[170:173], v[148:151], v[66:69]
	v_exp_f32_e32 v179, v205
	v_exp_f32_e32 v189, v206
	v_exp_f32_e32 v197, v207
	v_exp_f32_e32 v167, v208
	v_exp_f32_e32 v185, v209
	v_exp_f32_e32 v191, v210
	v_exp_f32_e32 v199, v211
	v_cvt_pk_bf16_f32 v174, v161, v179
	v_cvt_pk_bf16_f32 v175, v189, v197
	v_cvt_pk_bf16_f32 v176, v167, v185
	v_cvt_pk_bf16_f32 v177, v191, v199
	v_pk_add_f32 v[116:117], v[116:117], v[220:221]
	v_pk_add_f32 v[118:119], v[118:119], v[222:223]
	v_mfma_f32_16x16x32_bf16 v[62:65], v[98:101], v[174:177], v[62:65]
	v_pk_add_f32 v[108:109], v[108:109], v[112:113]
	v_mfma_f32_16x16x32_bf16 v[58:61], v[152:155], v[174:177], v[58:61]
	v_pk_add_f32 v[110:111], v[110:111], v[114:115]
	v_mfma_f32_16x16x32_bf16 v[54:57], v[156:159], v[174:177], v[54:57]
	v_pk_add_f32 v[116:117], v[116:117], v[118:119]
	v_mfma_f32_16x16x32_bf16 v[50:53], v[170:173], v[174:177], v[50:53]
	v_pk_add_f32 v[108:109], v[108:109], v[110:111]
	v_pk_add_f32 v[108:109], v[116:117], v[108:109]
	v_exp_f32_e32 v160, v136
	v_exp_f32_e32 v178, v137
	v_exp_f32_e32 v188, v138
	v_exp_f32_e32 v196, v139
	v_pk_add_f32 v[104:105], v[104:105], v[108:109]
	v_pk_add_f32 v[110:111], v[188:189], v[196:197]
	v_pk_add_f32 v[108:109], v[160:161], v[178:179]
	v_exp_f32_e32 v166, v140
	v_exp_f32_e32 v184, v141
	v_exp_f32_e32 v190, v142
	v_exp_f32_e32 v198, v143
	v_pk_add_f32 v[108:109], v[108:109], v[110:111]
	v_pk_add_f32 v[112:113], v[190:191], v[198:199]
	v_pk_add_f32 v[110:111], v[166:167], v[184:185]
	v_pk_add_f32 v[110:111], v[110:111], v[112:113]
	v_pk_add_f32 v[108:109], v[108:109], v[110:111]
	v_pk_add_f32 v[104:105], v[104:105], v[108:109]
	v_cvt_pk_bf16_f32 v108, v160, v178
	v_cvt_pk_bf16_f32 v109, v188, v196
	v_cvt_pk_bf16_f32 v110, v166, v184
	v_cvt_pk_bf16_f32 v111, v190, v198
	s_nop 1
	v_mfma_f32_16x16x32_bf16 v[38:41], v[98:101], v[108:111], v[38:41]
	v_mfma_f32_16x16x32_bf16 v[34:37], v[152:155], v[108:111], v[34:37]
	v_mfma_f32_16x16x32_bf16 v[30:33], v[156:159], v[108:111], v[30:33]
	v_mfma_f32_16x16x32_bf16 v[26:29], v[170:173], v[108:111], v[26:29]
	s_add_i32 s17, s17, 1
	s_add_i32 s39, s39, 64
	s_cmp_eq_u32 s37, s17
	s_cbranch_scc1 .LBB0_240
